# v14 + second item of each attention-only workgroup also static (items 128..255), dynamic queue starts at 256
# speedup vs baseline: 1.0123x; 1.0001x over previous
; __device__ __forceinline__ void phase_attn(const Params& p, LAS unsigned char* lds, unsigned* queue) {
;     ...
;         if (tid == 0) *tick = __hip_atomic_fetch_add(queue, 1u, __ATOMIC_RELAXED, __HIP_MEMORY_SCOPE_AGENT);
;         __syncthreads();
;         const int idx = (int)*tick;
;         if (idx >= 512) break;
.LBB0_333:
	s_and_saveexec_b64 s[4:5], s[92:93]
	s_cbranch_execz .LBB0_337
	s_mov_b64 s[8:9], exec
	v_mbcnt_lo_u32_b32 v2, s8, 0
	v_mbcnt_hi_u32_b32 v2, s9, v2
	v_cmp_eq_u32_e32 vcc, 0, v2
	s_and_saveexec_b64 s[6:7], vcc
	s_cbranch_execz .LBB0_336
	v_readfirstlane_b32 s98, v251
	s_cmpk_gt_i32 s2, 0x7f
	s_cbranch_scc0 .Lq_dyn
	s_cmp_eq_u32 s98, 1
	s_cbranch_scc0 .Lq_try2
	s_sub_i32 s0, s2, 0x80
	v_mov_b32_e32 v251, 2
	v_mov_b32_e32 v4, s0
	s_branch .LBB0_336
.Lq_try2:
	s_cmp_eq_u32 s98, 2
	s_cbranch_scc0 .Lq_dyn
	s_add_i32 s0, s2, 64
	s_and_b32 s0, s0, 0x7f
	s_add_i32 s0, s0, 0x80
	v_mov_b32_e32 v251, 0
	v_mov_b32_e32 v4, s0
	s_branch .LBB0_336
.Lq_dyn:
	s_bcnt1_i32_b64 s0, s[8:9]
	v_mov_b32_e32 v4, s0
	v_readlane_b32 s0, v255, 6
	v_readlane_b32 s1, v255, 7
	s_nop 4
	global_atomic_add v4, v3, v4, s[0:1] sc0
	s_waitcnt vmcnt(0)
	v_add_u32_e32 v4, 0x100, v4
